# diff attention main loop: softmax row-sum accumulated with packed f32 adds (v_pk_add_f32, 18 instead of 33 VALU ops per step), on top of direct HBM->LDS K/V staging
# speedup vs baseline: 1.0137x; 1.0055x over previous
; __device__ __forceinline__ unsigned cvtpk(float lo, float hi) { unsigned r; asm volatile("v_cvt_pk_bf16_f32 %0, %1, %2" : "=v"(r) : "v"(lo), "v"(hi)); return r; }
; __device__ __forceinline__ void finishSM(f32x16& p0, f32x16& p1, float alpha, float& l_reg, bf16x8& pa0, bf16x8& pa1, bf16x8& pa2, bf16x8& pa3) {
; #pragma unroll
;   for (int r = 0; r < 16; ++r) p1[r] = __builtin_amdgcn_exp2f(p1[r]);
;   float ps = 0;
; #pragma unroll
;   for (int r = 0; r < 16; ++r) ps += p0[r];
; #pragma unroll
;   for (int r = 0; r < 16; ++r) ps += p1[r];
;   { auto rr = __builtin_amdgcn_permlane32_swap(__float_as_uint(ps), __float_as_uint(ps), false, false);
;     ps = __uint_as_float(rr[0]) + __uint_as_float(rr[1]); }
;   l_reg = l_reg * alpha + ps;
;     ...
;   PK4(p0, 0, pa0); PK4(p0, 8, pa1); PK4(p1, 0, pa2); PK4(p1, 8, pa3);
;     ...
; }
; __device__ __forceinline__ bf16x8 scale_bf16x8(bf16x8 v, float c) {
;   u32x4 w = *reinterpret_cast<u32x4*>(&v), o;
; #pragma unroll
;   for (int i = 0; i < 4; ++i) { const float lo = __uint_as_float(w[i] << 16), hh = __uint_as_float(w[i] & 0xffff0000u); o[i] = cvtpk(lo * c, hh * c); }
;   return *reinterpret_cast<bf16x8*>(&o);
; }
; template <int ND0> __device__ __forceinline__ void qkt(f32x16& p0, f32x16& p1, const char* Ks, const bf16x8* qr, int r32, int hi, int cboff, const f32x16& ci) {
; #pragma unroll
;   for (int d0 = 0; d0 < ND0; ++d0) { int cb = cboff + (d0 * 16 + hi * 8) * 2;
;     bf16x8 b0 = *reinterpret_cast<const bf16x8*>(Ks + KSWZ(r32, cb));
;     bf16x8 b1 = *reinterpret_cast<const bf16x8*>(Ks + KSWZ(32 + r32, cb));
;     if (d0 == 0) { p0 = __builtin_amdgcn_mfma_f32_32x32x16_bf16(b0, qr[0], ci, 0, 0, 0); p1 = __builtin_amdgcn_mfma_f32_32x32x16_bf16(b1, qr[0], ci, 0, 0, 0); }
;     else { p0 = __builtin_amdgcn_mfma_f32_32x32x16_bf16(b0, qr[d0], p0, 0, 0, 0); p1 = __builtin_amdgcn_mfma_f32_32x32x16_bf16(b1, qr[d0], p1, 0, 0, 0); } }
; }
.LBB0_166:
	s_add_i32 s34, s68, 0
	v_add_u32_e32 v96, s34, v188
	ds_read_b128 v[210:213], v96 offset:24576
	ds_read_b128 v[96:99], v96 offset:16384
	v_add_u32_e32 v201, s34, v196
	v_exp_f32_e32 v206, v81
	v_exp_f32_e32 v207, v82
	v_exp_f32_e32 v208, v83
	s_waitcnt lgkmcnt(0)
	v_mfma_f32_32x32x16_bf16 v[112:127], v[96:99], v[128:131], v[64:79]
	v_exp_f32_e32 v209, v84
	v_exp_f32_e32 v87, v87
	v_exp_f32_e32 v214, v88
	v_exp_f32_e32 v220, v93
	v_exp_f32_e32 v221, v94
	v_exp_f32_e32 v95, v95
	v_mfma_f32_32x32x16_bf16 v[96:111], v[210:213], v[128:131], v[64:79]
	ds_read_b128 v[210:213], v201 offset:24576
	ds_read_b128 v[216:219], v201 offset:16384
	v_add_u32_e32 v201, s34, v190
	s_waitcnt lgkmcnt(0)
	v_mfma_f32_32x32x16_bf16 v[112:127], v[216:219], v[132:135], v[112:127]
	v_mfma_f32_32x32x16_bf16 v[96:111], v[210:213], v[132:135], v[96:111]
	ds_read_b128 v[210:213], v201 offset:24576
	ds_read_b128 v[216:219], v201 offset:16384
	v_add_u32_e32 v201, s34, v189
	s_waitcnt lgkmcnt(0)
	v_mfma_f32_32x32x16_bf16 v[112:127], v[216:219], v[136:139], v[112:127]
	v_mfma_f32_32x32x16_bf16 v[96:111], v[210:213], v[136:139], v[96:111]
	ds_read_b128 v[210:213], v201 offset:24576
	ds_read_b128 v[216:219], v201 offset:16384
	v_exp_f32_e32 v201, v80
	v_pk_add_f32 v[144:145], v[160:161], v[162:163]
	v_pk_add_f32 v[144:145], v[144:145], v[164:165]
	v_pk_add_f32 v[144:145], v[144:145], v[166:167]
	v_pk_add_f32 v[144:145], v[144:145], v[168:169]
	v_pk_add_f32 v[144:145], v[144:145], v[170:171]
	v_pk_add_f32 v[144:145], v[144:145], v[172:173]
	v_pk_add_f32 v[144:145], v[144:145], v[174:175]
	v_pk_add_f32 v[144:145], v[144:145], v[206:207]
	v_pk_add_f32 v[144:145], v[144:145], v[208:209]
	v_pk_add_f32 v[144:145], v[144:145], v[220:221]
	v_add_f32_e32 v80, v87, v214
	v_add_f32_e32 v80, v95, v80
	s_waitcnt lgkmcnt(1)
	v_mfma_f32_32x32x16_bf16 v[96:111], v[210:213], v[140:143], v[96:111]
	v_exp_f32_e32 v212, v85
	v_add_f32_e32 v80, v201, v80
	v_exp_f32_e32 v213, v86
	s_waitcnt lgkmcnt(0)
	v_mfma_f32_32x32x16_bf16 v[112:127], v[216:219], v[140:143], v[112:127]
	v_exp_f32_e32 v216, v89
	v_exp_f32_e32 v217, v90
	v_exp_f32_e32 v218, v91
	v_exp_f32_e32 v219, v92
	v_pk_add_f32 v[144:145], v[144:145], v[212:213]
	v_pk_add_f32 v[144:145], v[144:145], v[216:217]
	v_pk_add_f32 v[144:145], v[144:145], v[218:219]
	v_add_f32_e32 v80, v144, v80
	v_add_f32_e32 v210, v145, v80
	v_mov_b32_e32 v211, v210
	v_cvt_pk_bf16_f32 v80, v173, v175
	v_cvt_pk_bf16_f32 v81, v171, v174
	v_cvt_pk_bf16_f32 v82, v169, v172
	v_cvt_pk_bf16_f32 v83, v168, v170
	v_cvt_pk_bf16_f32 v88, v165, v167
	v_cvt_pk_bf16_f32 v89, v163, v166
	v_cvt_pk_bf16_f32 v90, v161, v164
	v_cvt_pk_bf16_f32 v91, v160, v162
	v_cvt_pk_bf16_f32 v84, v201, v206
	v_cvt_pk_bf16_f32 v85, v207, v208
	v_cvt_pk_bf16_f32 v86, v209, v212
	v_cvt_pk_bf16_f32 v87, v213, v87
	v_cvt_pk_bf16_f32 v92, v214, v216
	v_cvt_pk_bf16_f32 v93, v217, v218
	v_cvt_pk_bf16_f32 v94, v219, v220
	v_cvt_pk_bf16_f32 v95, v221, v95
	s_nop 1
	v_permlane32_swap_b32_e32 v210, v211
	v_permlane32_swap_b32_e32 v80, v82
	v_permlane32_swap_b32_e32 v81, v83
	v_permlane32_swap_b32_e32 v88, v90
	v_permlane32_swap_b32_e32 v89, v91
	v_permlane32_swap_b32_e32 v84, v86
	v_permlane32_swap_b32_e32 v85, v87
	v_permlane32_swap_b32_e32 v92, v94
	v_permlane32_swap_b32_e32 v93, v95
	s_andn2_b64 vcc, exec, s[10:11]
	v_add_u32_e32 v212, s56, v202
	s_cbranch_vccnz .LBB0_168
	v_add_u32_e32 v160, 0xc0, v212
	v_med3_i32 v161, v160, 0, v249
	v_med3_i32 v160, v160, s75, v250
	v_lshl_add_u32 v162, v160, 2, s69
	v_add_u32_e32 v160, 0xc1, v212
	v_med3_i32 v163, v160, 0, v249
	v_med3_i32 v160, v160, s75, v250
	v_lshl_add_u32 v164, v160, 2, s69
	v_add_u32_e32 v160, 0xc2, v212
	v_med3_i32 v165, v160, 0, v249
	v_med3_i32 v160, v160, s75, v250
	v_lshl_add_u32 v166, v160, 2, s69
	v_add_u32_e32 v160, 0xc3, v212
	v_med3_i32 v167, v160, 0, v249
	v_med3_i32 v160, v160, s75, v250
	v_lshl_add_u32 v161, v161, 2, s69
	v_lshl_add_u32 v163, v163, 2, s69
	v_lshl_add_u32 v165, v165, 2, s69
	v_lshl_add_u32 v167, v167, 2, s69
	v_lshl_add_u32 v168, v160, 2, s69
	ds_read_b32 v160, v161
	ds_read_b32 v162, v162 offset:128
	ds_read_b32 v161, v163
	ds_read_b32 v163, v164 offset:128
	ds_read_b32 v164, v165
	ds_read_b32 v166, v166 offset:128
	ds_read_b32 v165, v167
	ds_read_b32 v167, v168 offset:128
	v_add_u32_e32 v168, 0xc8, v212
	v_med3_i32 v169, v168, 0, v249
	v_med3_i32 v168, v168, s75, v250
	v_lshl_add_u32 v170, v168, 2, s69
	v_add_u32_e32 v168, 0xc9, v212
	v_med3_i32 v171, v168, 0, v249
	v_med3_i32 v168, v168, s75, v250
	v_lshl_add_u32 v172, v168, 2, s69
	v_add_u32_e32 v168, 0xca, v212
	v_med3_i32 v173, v168, 0, v249
	v_med3_i32 v168, v168, s75, v250
	v_add_u32_e32 v207, 0xd1, v212
	v_lshl_add_u32 v174, v168, 2, s69
	v_add_u32_e32 v168, 0xcb, v212
	v_med3_i32 v208, v207, 0, v249
	v_med3_i32 v207, v207, s75, v250
	v_med3_i32 v175, v168, 0, v249
	v_med3_i32 v168, v168, s75, v250
	v_lshl_add_u32 v213, v207, 2, s69
	v_add_u32_e32 v207, 0xd2, v212
	v_lshl_add_u32 v169, v169, 2, s69
	v_lshl_add_u32 v171, v171, 2, s69
	v_lshl_add_u32 v173, v173, 2, s69
	v_lshl_add_u32 v175, v175, 2, s69
	v_lshl_add_u32 v201, v168, 2, s69
	v_lshl_add_u32 v209, v208, 2, s69
	v_med3_i32 v208, v207, 0, v249
	v_med3_i32 v207, v207, s75, v250
	ds_read_b32 v168, v169
	ds_read_b32 v170, v170 offset:128
	ds_read_b32 v169, v171
	ds_read_b32 v171, v172 offset:128
	ds_read_b32 v172, v173
	ds_read_b32 v174, v174 offset:128
	ds_read_b32 v173, v175
	ds_read_b32 v175, v201 offset:128
	v_add_u32_e32 v201, 0xd0, v212
	v_lshl_add_u32 v217, v207, 2, s69
	v_add_u32_e32 v207, 0xd3, v212
	v_med3_i32 v206, v201, 0, v249
	v_lshl_add_u32 v214, v208, 2, s69
	v_med3_i32 v208, v207, 0, v249
	v_med3_i32 v201, v201, s75, v250
	v_lshl_add_u32 v206, v206, 2, s69
	v_med3_i32 v207, v207, s75, v250
	v_lshl_add_u32 v219, v208, 2, s69
	v_lshl_add_u32 v201, v201, 2, s69
	v_lshl_add_u32 v220, v207, 2, s69
	ds_read_b32 v206, v206
	ds_read_b32 v208, v201 offset:128
	ds_read_b32 v207, v209
	ds_read_b32 v209, v213 offset:128
	ds_read_b32 v216, v214
	ds_read_b32 v218, v217 offset:128
	ds_read_b32 v217, v219
	ds_read_b32 v219, v220 offset:128
	v_add_u32_e32 v214, 0xd9, v212
	v_med3_i32 v220, v214, 0, v249
	v_lshl_add_u32 v221, v220, 2, s69
	v_add_u32_e32 v220, 0xda, v212
	v_med3_i32 v222, v220, 0, v249
	v_med3_i32 v220, v220, s75, v250
	v_add_u32_e32 v201, 0xd8, v212
	v_lshl_add_u32 v226, v220, 2, s69
	v_add_u32_e32 v220, 0xdb, v212
	v_med3_i32 v213, v201, 0, v249
	v_lshl_add_u32 v223, v222, 2, s69
	v_med3_i32 v222, v220, 0, v249
	v_med3_i32 v220, v220, s75, v250
	v_med3_i32 v201, v201, s75, v250
	v_lshl_add_u32 v213, v213, 2, s69
	v_med3_i32 v214, v214, s75, v250
	v_lshl_add_u32 v225, v222, 2, s69
	v_lshl_add_u32 v227, v220, 2, s69
	v_lshl_add_u32 v201, v201, 2, s69
	v_lshl_add_u32 v214, v214, 2, s69
	ds_read_b32 v220, v213
	ds_read_b32 v222, v201 offset:128
	ds_read_b32 v224, v223
	ds_read_b32 v225, v225
	ds_read_b32 v221, v221
	ds_read_b32 v227, v227 offset:128
	ds_read_b32 v226, v226 offset:128
	ds_read_b32 v223, v214 offset:128
	s_waitcnt lgkmcnt(4)
	v_pk_add_f32 v[126:127], v[126:127], v[224:225]
	s_waitcnt lgkmcnt(3)
	v_pk_add_f32 v[124:125], v[124:125], v[220:221]
	v_pk_add_f32 v[122:123], v[122:123], v[216:217]
	v_pk_add_f32 v[120:121], v[120:121], v[206:207]
	v_pk_add_f32 v[118:119], v[118:119], v[172:173]
	v_pk_add_f32 v[116:117], v[116:117], v[168:169]
	v_pk_add_f32 v[114:115], v[114:115], v[164:165]
	v_pk_add_f32 v[112:113], v[112:113], v[160:161]
	s_waitcnt lgkmcnt(1)
	v_pk_add_f32 v[110:111], v[110:111], v[226:227]
	s_waitcnt lgkmcnt(0)
	v_pk_add_f32 v[108:109], v[108:109], v[222:223]
	v_pk_add_f32 v[106:107], v[106:107], v[218:219]
	v_pk_add_f32 v[104:105], v[104:105], v[208:209]
	v_pk_add_f32 v[102:103], v[102:103], v[174:175]
	v_pk_add_f32 v[100:101], v[100:101], v[170:171]
	v_pk_add_f32 v[98:99], v[98:99], v[166:167]
	v_pk_add_f32 v[96:97], v[96:97], v[162:163]

; __device__ __forceinline__ unsigned cvtpk(float lo, float hi) { unsigned r; asm volatile("v_cvt_pk_bf16_f32 %0, %1, %2" : "=v"(r) : "v"(lo), "v"(hi)); return r; }
; __device__ __forceinline__ void finishSM(f32x16& p0, f32x16& p1, float alpha, float& l_reg, bf16x8& pa0, bf16x8& pa1, bf16x8& pa2, bf16x8& pa3) {
; #pragma unroll
;   for (int r = 0; r < 16; ++r) p1[r] = __builtin_amdgcn_exp2f(p1[r]);
;   float ps = 0;
; #pragma unroll
;   for (int r = 0; r < 16; ++r) ps += p0[r];
; #pragma unroll
;   for (int r = 0; r < 16; ++r) ps += p1[r];
;   { auto rr = __builtin_amdgcn_permlane32_swap(__float_as_uint(ps), __float_as_uint(ps), false, false);
;     ps = __uint_as_float(rr[0]) + __uint_as_float(rr[1]); }
;   l_reg = l_reg * alpha + ps;
;     ...
;   PK4(p0, 0, pa0); PK4(p0, 8, pa1); PK4(p1, 0, pa2); PK4(p1, 8, pa3);
;     ...
; }
; __device__ __forceinline__ bf16x8 scale_bf16x8(bf16x8 v, float c) {
;   u32x4 w = *reinterpret_cast<u32x4*>(&v), o;
; #pragma unroll
;   for (int i = 0; i < 4; ++i) { const float lo = __uint_as_float(w[i] << 16), hh = __uint_as_float(w[i] & 0xffff0000u); o[i] = cvtpk(lo * c, hh * c); }
;   return *reinterpret_cast<bf16x8*>(&o);
; }
; template <int ND0> __device__ __forceinline__ void qkt(f32x16& p0, f32x16& p1, const char* Ks, const bf16x8* qr, int r32, int hi, int cboff, const f32x16& ci) {
; #pragma unroll
;   for (int d0 = 0; d0 < ND0; ++d0) { int cb = cboff + (d0 * 16 + hi * 8) * 2;
;     bf16x8 b0 = *reinterpret_cast<const bf16x8*>(Ks + KSWZ(r32, cb));
;     bf16x8 b1 = *reinterpret_cast<const bf16x8*>(Ks + KSWZ(32 + r32, cb));
;     if (d0 == 0) { p0 = __builtin_amdgcn_mfma_f32_32x32x16_bf16(b0, qr[0], ci, 0, 0, 0); p1 = __builtin_amdgcn_mfma_f32_32x32x16_bf16(b1, qr[0], ci, 0, 0, 0); }
;     else { p0 = __builtin_amdgcn_mfma_f32_32x32x16_bf16(b0, qr[d0], p0, 0, 0, 0); p1 = __builtin_amdgcn_mfma_f32_32x32x16_bf16(b1, qr[d0], p1, 0, 0, 0); } }
; }
.LBB0_177:
	v_exp_f32_e32 v168, v112
	v_exp_f32_e32 v169, v113
	v_exp_f32_e32 v170, v114
	v_exp_f32_e32 v171, v115
	v_exp_f32_e32 v172, v116
	v_exp_f32_e32 v173, v117
	v_exp_f32_e32 v174, v118
	v_exp_f32_e32 v175, v119
	v_exp_f32_e32 v206, v120
	v_exp_f32_e32 v207, v121
	v_exp_f32_e32 v208, v122
	v_exp_f32_e32 v209, v123
	v_exp_f32_e32 v217, v124
	v_exp_f32_e32 v218, v125
	v_exp_f32_e32 v219, v126
	v_exp_f32_e32 v220, v127
	v_add_u32_e32 v80, s79, v188
	ds_read_b128 v[160:163], v80 offset:24576
	ds_read_b128 v[80:83], v80 offset:16384
	v_add_u32_e32 v164, s79, v196
	v_exp_f32_e32 v96, v96
	v_exp_f32_e32 v97, v97
	v_exp_f32_e32 v98, v98
	s_waitcnt lgkmcnt(0)
	v_mfma_f32_32x32x16_bf16 v[112:127], v[80:83], v[128:131], v[64:79]
	v_exp_f32_e32 v99, v99
	v_exp_f32_e32 v100, v100
	v_exp_f32_e32 v101, v101
	v_exp_f32_e32 v102, v102
	v_exp_f32_e32 v103, v103
	v_mfma_f32_32x32x16_bf16 v[80:95], v[160:163], v[128:131], v[64:79]
	ds_read_b128 v[160:163], v164 offset:24576
	ds_read_b128 v[164:167], v164 offset:16384
	s_waitcnt lgkmcnt(1)
	v_mfma_f32_32x32x16_bf16 v[80:95], v[160:163], v[132:135], v[80:95]
	s_waitcnt lgkmcnt(0)
	v_mfma_f32_32x32x16_bf16 v[112:127], v[164:167], v[132:135], v[112:127]
	v_add_u32_e32 v164, s79, v190
	ds_read_b128 v[160:163], v164 offset:24576
	ds_read_b128 v[164:167], v164 offset:16384
	s_waitcnt lgkmcnt(1)
	v_mfma_f32_32x32x16_bf16 v[80:95], v[160:163], v[136:139], v[80:95]
	s_waitcnt lgkmcnt(0)
	v_mfma_f32_32x32x16_bf16 v[112:127], v[164:167], v[136:139], v[112:127]
	v_add_u32_e32 v164, s79, v189
	ds_read_b128 v[160:163], v164 offset:24576
	ds_read_b128 v[164:167], v164 offset:16384
	s_waitcnt lgkmcnt(1)
	v_mfma_f32_32x32x16_bf16 v[80:95], v[160:163], v[140:143], v[80:95]
	v_exp_f32_e32 v160, v104
	v_pk_add_f32 v[144:145], v[168:169], v[170:171]
	v_pk_add_f32 v[144:145], v[144:145], v[172:173]
	v_pk_add_f32 v[144:145], v[144:145], v[174:175]
	v_pk_add_f32 v[144:145], v[144:145], v[206:207]
	v_pk_add_f32 v[144:145], v[144:145], v[208:209]
	v_pk_add_f32 v[144:145], v[144:145], v[218:219]
	v_pk_add_f32 v[144:145], v[144:145], v[96:97]
	v_pk_add_f32 v[144:145], v[144:145], v[98:99]
	v_pk_add_f32 v[144:145], v[144:145], v[100:101]
	v_exp_f32_e32 v161, v105
	v_pk_add_f32 v[144:145], v[144:145], v[102:103]
	v_exp_f32_e32 v162, v106
	v_add_f32_e32 v104, v217, v220
	v_exp_f32_e32 v163, v107
	s_waitcnt lgkmcnt(0)
	v_mfma_f32_32x32x16_bf16 v[112:127], v[164:167], v[140:143], v[112:127]
	v_exp_f32_e32 v164, v108
	v_exp_f32_e32 v165, v109
	v_exp_f32_e32 v166, v110
	v_exp_f32_e32 v167, v111
	v_pk_add_f32 v[144:145], v[144:145], v[160:161]
	v_pk_add_f32 v[144:145], v[144:145], v[162:163]
	v_pk_add_f32 v[144:145], v[144:145], v[164:165]
	v_pk_add_f32 v[144:145], v[144:145], v[166:167]
	v_add_f32_e32 v104, v144, v104
	v_add_f32_e32 v215, v145, v104
	v_mov_b32_e32 v216, v215
	v_cvt_pk_bf16_f32 v104, v168, v169
	v_cvt_pk_bf16_f32 v105, v170, v171
	v_cvt_pk_bf16_f32 v106, v172, v173
	v_cvt_pk_bf16_f32 v107, v174, v175
	v_cvt_pk_bf16_f32 v108, v206, v207
	v_cvt_pk_bf16_f32 v109, v208, v209
	v_cvt_pk_bf16_f32 v110, v217, v218
	v_cvt_pk_bf16_f32 v111, v219, v220
	v_cvt_pk_bf16_f32 v96, v96, v97
	v_cvt_pk_bf16_f32 v97, v98, v99
	v_cvt_pk_bf16_f32 v98, v100, v101
	v_cvt_pk_bf16_f32 v99, v102, v103
	v_cvt_pk_bf16_f32 v100, v160, v161
	v_cvt_pk_bf16_f32 v101, v162, v163
	v_cvt_pk_bf16_f32 v102, v164, v165
	v_cvt_pk_bf16_f32 v103, v166, v167
	s_nop 1
	v_permlane32_swap_b32_e32 v215, v216
	v_permlane32_swap_b32_e32 v104, v106
	v_permlane32_swap_b32_e32 v105, v107
	v_permlane32_swap_b32_e32 v108, v110
	v_permlane32_swap_b32_e32 v109, v111
	v_permlane32_swap_b32_e32 v96, v98
	v_permlane32_swap_b32_e32 v97, v99
	v_permlane32_swap_b32_e32 v100, v102
	v_permlane32_swap_b32_e32 v101, v103
	s_andn2_b64 vcc, exec, s[10:11]
	s_cbranch_vccnz .LBB0_179
	v_add_u32_e32 v160, 0x100, v212
	v_med3_i32 v161, v160, 0, v249
	v_med3_i32 v160, v160, s75, v250
	v_lshl_add_u32 v162, v160, 2, s69
	v_add_u32_e32 v160, 0x101, v212
	v_med3_i32 v163, v160, 0, v249
	v_med3_i32 v160, v160, s75, v250
	v_lshl_add_u32 v164, v160, 2, s69
	v_add_u32_e32 v160, 0x102, v212
	v_med3_i32 v165, v160, 0, v249
	v_med3_i32 v160, v160, s75, v250
	v_lshl_add_u32 v166, v160, 2, s69
	v_add_u32_e32 v160, 0x103, v212
	v_med3_i32 v167, v160, 0, v249
	v_med3_i32 v160, v160, s75, v250
	v_lshl_add_u32 v161, v161, 2, s69
	v_lshl_add_u32 v163, v163, 2, s69
	v_lshl_add_u32 v165, v165, 2, s69
	v_lshl_add_u32 v167, v167, 2, s69
	v_lshl_add_u32 v168, v160, 2, s69
	ds_read_b32 v160, v161
	ds_read_b32 v162, v162 offset:128
	ds_read_b32 v161, v163
	ds_read_b32 v163, v164 offset:128
	ds_read_b32 v164, v165
	ds_read_b32 v166, v166 offset:128
	ds_read_b32 v165, v167
	ds_read_b32 v167, v168 offset:128
	v_add_u32_e32 v168, 0x108, v212
	v_med3_i32 v169, v168, 0, v249
	v_med3_i32 v168, v168, s75, v250
	v_lshl_add_u32 v170, v168, 2, s69
	v_add_u32_e32 v168, 0x109, v212
	v_med3_i32 v171, v168, 0, v249
	v_med3_i32 v168, v168, s75, v250
	v_lshl_add_u32 v172, v168, 2, s69
	v_add_u32_e32 v168, 0x10a, v212
	v_med3_i32 v173, v168, 0, v249
	v_med3_i32 v168, v168, s75, v250
	v_lshl_add_u32 v174, v168, 2, s69
	v_add_u32_e32 v168, 0x10b, v212
	v_med3_i32 v175, v168, 0, v249
	v_med3_i32 v168, v168, s75, v250
	v_lshl_add_u32 v169, v169, 2, s69
	v_lshl_add_u32 v171, v171, 2, s69
	v_lshl_add_u32 v173, v173, 2, s69
	v_lshl_add_u32 v175, v175, 2, s69
	v_lshl_add_u32 v206, v168, 2, s69
	ds_read_b32 v168, v169
	ds_read_b32 v170, v170 offset:128
	ds_read_b32 v169, v171
	ds_read_b32 v171, v172 offset:128
	ds_read_b32 v172, v173
	ds_read_b32 v174, v174 offset:128
	ds_read_b32 v173, v175
	ds_read_b32 v175, v206 offset:128
	v_add_u32_e32 v206, 0x110, v212
	v_med3_i32 v207, v206, 0, v249
	v_med3_i32 v206, v206, s75, v250
	v_lshl_add_u32 v208, v206, 2, s69
	v_add_u32_e32 v206, 0x111, v212
	v_med3_i32 v209, v206, 0, v249
	v_med3_i32 v206, v206, s75, v250
	v_lshl_add_u32 v217, v206, 2, s69
	v_add_u32_e32 v206, 0x112, v212
	v_med3_i32 v218, v206, 0, v249
	v_med3_i32 v206, v206, s75, v250
	v_lshl_add_u32 v219, v206, 2, s69
	v_add_u32_e32 v206, 0x113, v212
	v_add_u32_e32 v223, 0x119, v212
	v_med3_i32 v220, v206, 0, v249
	v_med3_i32 v224, v223, 0, v249
	v_med3_i32 v223, v223, s75, v250
	v_lshl_add_u32 v207, v207, 2, s69
	v_lshl_add_u32 v209, v209, 2, s69
	v_lshl_add_u32 v218, v218, 2, s69
	v_med3_i32 v206, v206, s75, v250
	v_lshl_add_u32 v221, v220, 2, s69
	v_lshl_add_u32 v230, v223, 2, s69
	v_add_u32_e32 v223, 0x11a, v212
	v_lshl_add_u32 v222, v206, 2, s69
	ds_read_b32 v206, v207
	ds_read_b32 v208, v208 offset:128
	ds_read_b32 v207, v209
	ds_read_b32 v209, v217 offset:128
	ds_read_b32 v218, v218
	ds_read_b32 v220, v219 offset:128
	ds_read_b32 v219, v221
	ds_read_b32 v221, v222 offset:128
	v_add_u32_e32 v217, 0x118, v212
	v_lshl_add_u32 v225, v224, 2, s69
	v_med3_i32 v224, v223, 0, v249
	v_med3_i32 v223, v223, s75, v250
	v_add_u32_e32 v212, 0x11b, v212
	v_med3_i32 v222, v217, 0, v249
	v_lshl_add_u32 v228, v223, 2, s69
	v_med3_i32 v223, v212, 0, v249
	v_med3_i32 v217, v217, s75, v250
	v_lshl_add_u32 v222, v222, 2, s69
	v_lshl_add_u32 v226, v224, 2, s69
	v_med3_i32 v212, v212, s75, v250
	v_lshl_add_u32 v223, v223, 2, s69
	v_lshl_add_u32 v217, v217, 2, s69
	v_lshl_add_u32 v212, v212, 2, s69
	ds_read_b32 v222, v222
	ds_read_b32 v224, v217 offset:128
	ds_read_b32 v226, v226
	ds_read_b32 v227, v223
	ds_read_b32 v223, v225
	ds_read_b32 v229, v212 offset:128
	ds_read_b32 v228, v228 offset:128
	ds_read_b32 v225, v230 offset:128
	s_waitcnt lgkmcnt(4)
	v_pk_add_f32 v[126:127], v[126:127], v[226:227]
	s_waitcnt lgkmcnt(3)
	v_pk_add_f32 v[124:125], v[124:125], v[222:223]
	v_pk_add_f32 v[122:123], v[122:123], v[218:219]
	v_pk_add_f32 v[120:121], v[120:121], v[206:207]
	v_pk_add_f32 v[118:119], v[118:119], v[172:173]
	v_pk_add_f32 v[116:117], v[116:117], v[168:169]
	v_pk_add_f32 v[114:115], v[114:115], v[164:165]
	v_pk_add_f32 v[112:113], v[112:113], v[160:161]
	s_waitcnt lgkmcnt(1)
	v_pk_add_f32 v[94:95], v[94:95], v[228:229]
	s_waitcnt lgkmcnt(0)
	v_pk_add_f32 v[92:93], v[92:93], v[224:225]
	v_pk_add_f32 v[90:91], v[90:91], v[220:221]
	v_pk_add_f32 v[88:89], v[88:89], v[208:209]
	v_pk_add_f32 v[86:87], v[86:87], v[174:175]
	v_pk_add_f32 v[84:85], v[84:85], v[170:171]
	v_pk_add_f32 v[82:83], v[82:83], v[166:167]
	v_pk_add_f32 v[80:81], v[80:81], v[162:163]
